# peeled first K iteration (swiglu, w_in, q): counted vmcnt waits raised by the 2 ssq staging loads issued in that iteration, restoring the original prefetch slack
# baseline (speedup 1.0000x reference)
.Lswi_nobar:
.Lpeel_357:
	s_add_i32 s86, s42, 2
	s_add_u32 s29, s16, 0xfffc0080
	s_addc_u32 s37, s17, -1
	s_add_i32 s74, 0, 0x10000
	s_cmp_eq_u32 s20, s42
	s_cselect_b32 s73, s9, s37
	s_cselect_b32 s72, s13, s29
	v_add_u32_e32 v170, s74, v179
	s_cselect_b32 s43, s28, s57
	s_cselect_b32 s42, s39, s56
	s_add_i32 s29, 0, 0x14000
	ds_read_b128 v[130:133], v170
	ds_read_b128 v[180:183], v170 offset:1024
	ds_read_b128 v[184:187], v170 offset:2048
	ds_read_b128 v[188:191], v170 offset:3072
	v_add_u32_e32 v170, s29, v179
	ds_read_b128 v[192:195], v170
	ds_read_b128 v[196:199], v170 offset:1024
	ds_read_b128 v[204:207], v170 offset:2048
	ds_read_b128 v[208:211], v170 offset:3072
	s_add_i32 m0, s4, 0xc000
	ds_read_b128 v[212:215], v143
	ds_read_b128 v[216:219], v143 offset:1024
	ds_read_b128 v[220:223], v143 offset:2048
	ds_read_b128 v[224:227], v143 offset:3072
	ds_read_b128 v[228:231], v143 offset:4096
	ds_read_b128 v[232:235], v143 offset:5120
	ds_read_b128 v[236:239], v143 offset:6144
	ds_read_b128 v[240:243], v143 offset:7168
	global_load_lds_dwordx4 v174, s[16:17]
	s_add_i32 m0, s4, 0xe000
	s_nop 0
	global_load_lds_dwordx4 v176, s[16:17]
	s_waitcnt vmcnt(8)
	s_waitcnt lgkmcnt(0)
	s_setprio 1
	s_barrier
	v_mfma_f32_16x16x32_bf16 v[126:129], v[130:133], v[212:215], 0
	v_mfma_f32_16x16x32_bf16 v[118:121], v[184:187], v[212:215], 0
	v_mfma_f32_16x16x32_bf16 v[110:113], v[130:133], v[220:223], 0
	v_mfma_f32_16x16x32_bf16 v[102:105], v[184:187], v[220:223], 0
	v_mfma_f32_16x16x32_bf16 v[94:97], v[130:133], v[228:231], 0
	v_mfma_f32_16x16x32_bf16 v[86:89], v[184:187], v[228:231], 0
	v_mfma_f32_16x16x32_bf16 v[78:81], v[130:133], v[236:239], 0
	v_mfma_f32_16x16x32_bf16 v[70:73], v[184:187], v[236:239], 0
	v_mfma_f32_16x16x32_bf16 v[126:129], v[180:183], v[216:219], v[126:129]
	v_mfma_f32_16x16x32_bf16 v[118:121], v[188:191], v[216:219], v[118:121]
	v_mfma_f32_16x16x32_bf16 v[110:113], v[180:183], v[224:227], v[110:113]
	v_mfma_f32_16x16x32_bf16 v[102:105], v[188:191], v[224:227], v[102:105]
	v_mfma_f32_16x16x32_bf16 v[94:97], v[180:183], v[232:235], v[94:97]
	v_mfma_f32_16x16x32_bf16 v[86:89], v[188:191], v[232:235], v[86:89]
	v_mfma_f32_16x16x32_bf16 v[78:81], v[180:183], v[240:243], v[78:81]
	v_mfma_f32_16x16x32_bf16 v[70:73], v[188:191], v[240:243], v[70:73]
	v_mfma_f32_16x16x32_bf16 v[122:125], v[192:195], v[212:215], 0
	v_mfma_f32_16x16x32_bf16 v[114:117], v[204:207], v[212:215], 0
	v_mfma_f32_16x16x32_bf16 v[106:109], v[192:195], v[220:223], 0
	v_mfma_f32_16x16x32_bf16 v[98:101], v[204:207], v[220:223], 0
	v_mfma_f32_16x16x32_bf16 v[90:93], v[192:195], v[228:231], 0
	v_mfma_f32_16x16x32_bf16 v[82:85], v[204:207], v[228:231], 0
	v_mfma_f32_16x16x32_bf16 v[74:77], v[192:195], v[236:239], 0
	v_mfma_f32_16x16x32_bf16 v[66:69], v[204:207], v[236:239], 0
	v_mfma_f32_16x16x32_bf16 v[122:125], v[196:199], v[216:219], v[122:125]
	v_mfma_f32_16x16x32_bf16 v[114:117], v[208:211], v[216:219], v[114:117]
	v_mfma_f32_16x16x32_bf16 v[106:109], v[196:199], v[224:227], v[106:109]
	v_mfma_f32_16x16x32_bf16 v[98:101], v[208:211], v[224:227], v[98:101]
	v_mfma_f32_16x16x32_bf16 v[90:93], v[196:199], v[232:235], v[90:93]
	v_mfma_f32_16x16x32_bf16 v[82:85], v[208:211], v[232:235], v[82:85]
	v_mfma_f32_16x16x32_bf16 v[74:77], v[196:199], v[240:243], v[74:77]
	v_mfma_f32_16x16x32_bf16 v[66:69], v[208:211], v[240:243], v[66:69]
	s_barrier
	s_setprio 0
	s_add_i32 s37, s74, s84
	v_lshl_add_u64 v[244:245], s[42:43], 0, v[138:139]
	s_mov_b32 m0, s37
	ds_read_b128 v[212:215], v143 offset:16384
	ds_read_b128 v[216:219], v143 offset:17408
	ds_read_b128 v[220:223], v143 offset:18432
	ds_read_b128 v[224:227], v143 offset:19456
	ds_read_b128 v[228:231], v143 offset:20480
	ds_read_b128 v[232:235], v143 offset:21504
	ds_read_b128 v[236:239], v143 offset:22528
	ds_read_b128 v[240:243], v143 offset:23552
	global_load_lds_dwordx4 v[244:245], off
	s_add_i32 m0, s37, 0x2000
	s_add_u32 s74, s42, 0x40000
	v_lshl_add_u64 v[246:247], s[42:43], 0, v[134:135]
	s_addc_u32 s75, s43, 0
	s_add_i32 s29, s29, s84
	global_load_lds_dwordx4 v[246:247], off
	s_mov_b32 m0, s29
	v_lshl_add_u64 v[170:171], s[72:73], 0, v[136:137]
	global_load_lds_dwordx4 v138, s[74:75]
	s_add_i32 m0, s29, 0x2000
	s_nop 0
	global_load_lds_dwordx4 v134, s[74:75]
	v_lshl_add_u64 v[248:249], s[72:73], 0, v[140:141]
	s_mov_b32 m0, s4
	s_nop 0
	global_load_lds_dwordx4 v[248:249], off
	s_mov_b32 m0, s5
	s_nop 0
	global_load_lds_dwordx4 v[170:171], off
	s_lshl_b32 s101, s38, 14
	s_add_i32 s101, s101, s84
	s_add_u32 s100, s66, s101
	s_addc_u32 s101, s67, 0
	v_lshlrev_b32_e32 v172, 4, v163
	v_add_u32_e32 v173, 0x2000, v172
	s_add_i32 m0, s84, 0x20000
	s_nop 0
	global_load_lds_dwordx4 v172, s[100:101]
	s_add_i32 m0, s84, 0x22000
	s_nop 0
	global_load_lds_dwordx4 v173, s[100:101]
	s_waitcnt vmcnt(10)
	s_waitcnt lgkmcnt(0)
	s_setprio 1
	s_barrier
	v_mfma_f32_16x16x32_bf16 v[62:65], v[130:133], v[212:215], 0
	v_mfma_f32_16x16x32_bf16 v[54:57], v[184:187], v[212:215], 0
	v_mfma_f32_16x16x32_bf16 v[46:49], v[130:133], v[220:223], 0
	v_mfma_f32_16x16x32_bf16 v[38:41], v[184:187], v[220:223], 0
	v_mfma_f32_16x16x32_bf16 v[30:33], v[130:133], v[228:231], 0
	v_mfma_f32_16x16x32_bf16 v[22:25], v[184:187], v[228:231], 0
	v_mfma_f32_16x16x32_bf16 v[14:17], v[130:133], v[236:239], 0
	v_mfma_f32_16x16x32_bf16 v[6:9], v[184:187], v[236:239], 0
	v_mfma_f32_16x16x32_bf16 v[62:65], v[180:183], v[216:219], v[62:65]
	v_mfma_f32_16x16x32_bf16 v[54:57], v[188:191], v[216:219], v[54:57]
	v_mfma_f32_16x16x32_bf16 v[46:49], v[180:183], v[224:227], v[46:49]
	v_mfma_f32_16x16x32_bf16 v[38:41], v[188:191], v[224:227], v[38:41]
	v_mfma_f32_16x16x32_bf16 v[30:33], v[180:183], v[232:235], v[30:33]
	v_mfma_f32_16x16x32_bf16 v[22:25], v[188:191], v[232:235], v[22:25]
	v_mfma_f32_16x16x32_bf16 v[14:17], v[180:183], v[240:243], v[14:17]
	v_mfma_f32_16x16x32_bf16 v[6:9], v[188:191], v[240:243], v[6:9]
	v_mfma_f32_16x16x32_bf16 v[58:61], v[192:195], v[212:215], 0
	v_mfma_f32_16x16x32_bf16 v[50:53], v[204:207], v[212:215], 0
	v_mfma_f32_16x16x32_bf16 v[42:45], v[192:195], v[220:223], 0
	v_mfma_f32_16x16x32_bf16 v[34:37], v[204:207], v[220:223], 0
	v_mfma_f32_16x16x32_bf16 v[26:29], v[192:195], v[228:231], 0
	v_mfma_f32_16x16x32_bf16 v[18:21], v[204:207], v[228:231], 0
	v_mfma_f32_16x16x32_bf16 v[10:13], v[192:195], v[236:239], 0
	v_mfma_f32_16x16x32_bf16 v[2:5], v[204:207], v[236:239], 0
	v_mfma_f32_16x16x32_bf16 v[58:61], v[196:199], v[216:219], v[58:61]
	v_mfma_f32_16x16x32_bf16 v[50:53], v[208:211], v[216:219], v[50:53]
	v_mfma_f32_16x16x32_bf16 v[42:45], v[196:199], v[224:227], v[42:45]
	v_mfma_f32_16x16x32_bf16 v[34:37], v[208:211], v[224:227], v[34:37]
	v_mfma_f32_16x16x32_bf16 v[26:29], v[196:199], v[232:235], v[26:29]
	v_mfma_f32_16x16x32_bf16 v[18:21], v[208:211], v[232:235], v[18:21]
	v_mfma_f32_16x16x32_bf16 v[10:13], v[196:199], v[240:243], v[10:13]
	v_mfma_f32_16x16x32_bf16 v[2:5], v[208:211], v[240:243], v[2:5]
	s_barrier
	s_setprio 0
	s_add_i32 s29, 0, 0x18000
	v_add_u32_e32 v172, s29, v179
	s_add_i32 s37, 0, 0x1c000
	ds_read_b128 v[130:133], v172
	ds_read_b128 v[180:183], v172 offset:1024
	ds_read_b128 v[184:187], v172 offset:2048
	ds_read_b128 v[188:191], v172 offset:3072
	v_add_u32_e32 v172, s37, v179
	ds_read_b128 v[192:195], v172
	ds_read_b128 v[196:199], v172 offset:1024
	ds_read_b128 v[204:207], v172 offset:2048
	ds_read_b128 v[208:211], v172 offset:3072
	s_add_u32 s72, s72, 0x40000
	s_addc_u32 s73, s73, 0
	s_mov_b32 m0, s93
	ds_read_b128 v[212:215], v143 offset:32768
	ds_read_b128 v[216:219], v143 offset:33792
	ds_read_b128 v[220:223], v143 offset:34816
	ds_read_b128 v[224:227], v143 offset:35840
	ds_read_b128 v[228:231], v143 offset:36864
	ds_read_b128 v[232:235], v143 offset:37888
	ds_read_b128 v[236:239], v143 offset:38912
	ds_read_b128 v[240:243], v143 offset:39936
	global_load_lds_dwordx4 v140, s[72:73]
	s_mov_b32 m0, s33
	s_nop 0
	global_load_lds_dwordx4 v136, s[72:73]
	s_waitcnt vmcnt(10)
	s_waitcnt lgkmcnt(0)
	s_setprio 1
	s_barrier
	v_mfma_f32_16x16x32_bf16 v[126:129], v[130:133], v[212:215], v[126:129]
	v_mfma_f32_16x16x32_bf16 v[118:121], v[184:187], v[212:215], v[118:121]
	v_mfma_f32_16x16x32_bf16 v[110:113], v[130:133], v[220:223], v[110:113]
	v_mfma_f32_16x16x32_bf16 v[102:105], v[184:187], v[220:223], v[102:105]
	v_mfma_f32_16x16x32_bf16 v[94:97], v[130:133], v[228:231], v[94:97]
	v_mfma_f32_16x16x32_bf16 v[86:89], v[184:187], v[228:231], v[86:89]
	v_mfma_f32_16x16x32_bf16 v[78:81], v[130:133], v[236:239], v[78:81]
	v_mfma_f32_16x16x32_bf16 v[70:73], v[184:187], v[236:239], v[70:73]
	v_mfma_f32_16x16x32_bf16 v[126:129], v[180:183], v[216:219], v[126:129]
	v_mfma_f32_16x16x32_bf16 v[118:121], v[188:191], v[216:219], v[118:121]
	v_mfma_f32_16x16x32_bf16 v[110:113], v[180:183], v[224:227], v[110:113]
	v_mfma_f32_16x16x32_bf16 v[102:105], v[188:191], v[224:227], v[102:105]
	v_mfma_f32_16x16x32_bf16 v[94:97], v[180:183], v[232:235], v[94:97]
	v_mfma_f32_16x16x32_bf16 v[86:89], v[188:191], v[232:235], v[86:89]
	v_mfma_f32_16x16x32_bf16 v[78:81], v[180:183], v[240:243], v[78:81]
	v_mfma_f32_16x16x32_bf16 v[70:73], v[188:191], v[240:243], v[70:73]
	v_mfma_f32_16x16x32_bf16 v[122:125], v[192:195], v[212:215], v[122:125]
	v_mfma_f32_16x16x32_bf16 v[114:117], v[204:207], v[212:215], v[114:117]
	v_mfma_f32_16x16x32_bf16 v[106:109], v[192:195], v[220:223], v[106:109]
	v_mfma_f32_16x16x32_bf16 v[98:101], v[204:207], v[220:223], v[98:101]
	v_mfma_f32_16x16x32_bf16 v[90:93], v[192:195], v[228:231], v[90:93]
	v_mfma_f32_16x16x32_bf16 v[82:85], v[204:207], v[228:231], v[82:85]
	v_mfma_f32_16x16x32_bf16 v[74:77], v[192:195], v[236:239], v[74:77]
	v_mfma_f32_16x16x32_bf16 v[66:69], v[204:207], v[236:239], v[66:69]
	v_mfma_f32_16x16x32_bf16 v[122:125], v[196:199], v[216:219], v[122:125]
	v_mfma_f32_16x16x32_bf16 v[114:117], v[208:211], v[216:219], v[114:117]
	v_mfma_f32_16x16x32_bf16 v[106:109], v[196:199], v[224:227], v[106:109]
	v_mfma_f32_16x16x32_bf16 v[98:101], v[208:211], v[224:227], v[98:101]
	v_mfma_f32_16x16x32_bf16 v[90:93], v[196:199], v[232:235], v[90:93]
	v_mfma_f32_16x16x32_bf16 v[82:85], v[208:211], v[232:235], v[82:85]
	v_mfma_f32_16x16x32_bf16 v[74:77], v[196:199], v[240:243], v[74:77]
	v_mfma_f32_16x16x32_bf16 v[66:69], v[208:211], v[240:243], v[66:69]
	s_barrier
	s_setprio 0
	s_add_i32 s29, s29, s84
	v_lshl_add_u64 v[172:173], v[244:245], 0, s[24:25]
	s_mov_b32 m0, s29
	ds_read_b128 v[212:215], v143 offset:49152
	ds_read_b128 v[216:219], v143 offset:50176
	ds_read_b128 v[220:223], v143 offset:51200
	ds_read_b128 v[224:227], v143 offset:52224
	ds_read_b128 v[228:231], v143 offset:53248
	ds_read_b128 v[232:235], v143 offset:54272
	ds_read_b128 v[236:239], v143 offset:55296
	ds_read_b128 v[240:243], v143 offset:56320
	global_load_lds_dwordx4 v[172:173], off
	s_add_i32 m0, s29, 0x2000
	s_add_u32 s42, s42, 0x40080
	v_lshl_add_u64 v[172:173], v[246:247], 0, s[24:25]
	s_addc_u32 s43, s43, 0
	s_add_i32 s29, s37, s84
	global_load_lds_dwordx4 v[172:173], off
	s_mov_b32 m0, s29
	v_lshl_add_u64 v[170:171], v[170:171], 0, s[24:25]
	global_load_lds_dwordx4 v138, s[42:43]
	s_add_i32 m0, s29, 0x2000
	s_nop 0
	global_load_lds_dwordx4 v134, s[42:43]
	v_lshl_add_u64 v[172:173], v[248:249], 0, s[24:25]
	s_mov_b32 m0, s97
	s_nop 0
	global_load_lds_dwordx4 v[172:173], off
	s_mov_b32 m0, s3
	s_nop 0
	global_load_lds_dwordx4 v[170:171], off
	s_waitcnt vmcnt(8)
	s_waitcnt lgkmcnt(0)
	s_setprio 1
	s_barrier
	v_mfma_f32_16x16x32_bf16 v[62:65], v[130:133], v[212:215], v[62:65]
	v_mfma_f32_16x16x32_bf16 v[54:57], v[184:187], v[212:215], v[54:57]
	v_mfma_f32_16x16x32_bf16 v[46:49], v[130:133], v[220:223], v[46:49]
	v_mfma_f32_16x16x32_bf16 v[38:41], v[184:187], v[220:223], v[38:41]
	v_mfma_f32_16x16x32_bf16 v[30:33], v[130:133], v[228:231], v[30:33]
	v_mfma_f32_16x16x32_bf16 v[22:25], v[184:187], v[228:231], v[22:25]
	v_mfma_f32_16x16x32_bf16 v[14:17], v[130:133], v[236:239], v[14:17]
	v_mfma_f32_16x16x32_bf16 v[6:9], v[184:187], v[236:239], v[6:9]
	v_mfma_f32_16x16x32_bf16 v[62:65], v[180:183], v[216:219], v[62:65]
	v_mfma_f32_16x16x32_bf16 v[54:57], v[188:191], v[216:219], v[54:57]
	v_mfma_f32_16x16x32_bf16 v[46:49], v[180:183], v[224:227], v[46:49]
	v_mfma_f32_16x16x32_bf16 v[38:41], v[188:191], v[224:227], v[38:41]
	v_mfma_f32_16x16x32_bf16 v[30:33], v[180:183], v[232:235], v[30:33]
	v_mfma_f32_16x16x32_bf16 v[22:25], v[188:191], v[232:235], v[22:25]
	v_mfma_f32_16x16x32_bf16 v[14:17], v[180:183], v[240:243], v[14:17]
	v_mfma_f32_16x16x32_bf16 v[6:9], v[188:191], v[240:243], v[6:9]
	v_mfma_f32_16x16x32_bf16 v[58:61], v[192:195], v[212:215], v[58:61]
	v_mfma_f32_16x16x32_bf16 v[50:53], v[204:207], v[212:215], v[50:53]
	v_mfma_f32_16x16x32_bf16 v[42:45], v[192:195], v[220:223], v[42:45]
	v_mfma_f32_16x16x32_bf16 v[34:37], v[204:207], v[220:223], v[34:37]
	v_mfma_f32_16x16x32_bf16 v[26:29], v[192:195], v[228:231], v[26:29]
	v_mfma_f32_16x16x32_bf16 v[18:21], v[204:207], v[228:231], v[18:21]
	v_mfma_f32_16x16x32_bf16 v[10:13], v[192:195], v[236:239], v[10:13]
	v_mfma_f32_16x16x32_bf16 v[2:5], v[204:207], v[236:239], v[2:5]
	v_mfma_f32_16x16x32_bf16 v[58:61], v[196:199], v[216:219], v[58:61]
	v_mfma_f32_16x16x32_bf16 v[50:53], v[208:211], v[216:219], v[50:53]
	v_mfma_f32_16x16x32_bf16 v[42:45], v[196:199], v[224:227], v[42:45]
	v_mfma_f32_16x16x32_bf16 v[34:37], v[208:211], v[224:227], v[34:37]
	v_mfma_f32_16x16x32_bf16 v[26:29], v[196:199], v[232:235], v[26:29]
	v_mfma_f32_16x16x32_bf16 v[18:21], v[208:211], v[232:235], v[18:21]
	v_mfma_f32_16x16x32_bf16 v[10:13], v[196:199], v[240:243], v[10:13]
	v_mfma_f32_16x16x32_bf16 v[2:5], v[208:211], v[240:243], v[2:5]
	s_barrier
	s_setprio 0
	s_lshl_b32 s100, s84, 1
	v_lshl_add_u32 v204, v163, 5, s100
	v_add_u32_e32 v204, 0x20000, v204
	ds_read_b128 v[208:211], v204
	ds_read_b128 v[212:215], v204 offset:16
	s_waitcnt lgkmcnt(0)
	v_add_f32_e32 v208, v208, v209
	v_add_f32_e32 v210, v210, v211
	v_add_f32_e32 v212, v212, v213
	v_add_f32_e32 v214, v214, v215
	v_add_f32_e32 v208, v208, v210
	v_add_f32_e32 v212, v212, v214
	v_add_f32_e32 v208, v208, v212
	v_mov_b32_e32 v209, 0x358637bd
	s_nop 0
	v_add_f32_dpp v208, v208, v208 quad_perm:[1,0,3,2] row_mask:0xf bank_mask:0xf
	v_fmamk_f32 v208, v208, 0x3a800000, v209
	v_rsq_f32_e32 v209, v208
	s_nop 0
	v_mul_f32_e32 v209, 0xbfb8aa3b, v209
	ds_write_b64 v204, v[208:209]
	s_add_u32 s16, s16, 0x100
	s_addc_u32 s17, s17, 0
	s_add_u32 s56, s56, 0x100
	s_addc_u32 s57, s57, 0
	s_cmp_ge_i32 s86, s23
	s_mov_b32 s42, s86
	s_cbranch_scc0 .LBB7_357
	s_branch .Lpeelx_357
	.p2align	6

.Lpeel_523:
	s_add_i32 s56, s42, 2
	s_add_u32 s29, s16, 0xfffc0080
	s_addc_u32 s37, s17, -1
	s_add_i32 s57, 0, 0x10000
	s_cmp_eq_u32 s84, s42
	s_cselect_b32 s45, s13, s37
	s_cselect_b32 s44, s15, s29
	v_add_u32_e32 v0, s57, v195
	s_cselect_b32 s43, s38, s49
	s_cselect_b32 s42, s39, s48
	s_add_i32 s29, 0, 0x14000
	ds_read_b128 v[130:133], v0
	ds_read_b128 v[150:153], v0 offset:1024
	ds_read_b128 v[154:157], v0 offset:2048
	ds_read_b128 v[158:161], v0 offset:3072
	v_add_u32_e32 v0, s29, v195
	ds_read_b128 v[174:177], v0
	ds_read_b128 v[178:181], v0 offset:1024
	ds_read_b128 v[182:185], v0 offset:2048
	ds_read_b128 v[186:189], v0 offset:3072
	s_add_i32 m0, s5, 0xc000
	ds_read_b128 v[190:193], v196
	ds_read_b128 v[204:207], v196 offset:1024
	ds_read_b128 v[208:211], v196 offset:2048
	ds_read_b128 v[212:215], v196 offset:3072
	ds_read_b128 v[216:219], v196 offset:4096
	ds_read_b128 v[220:223], v196 offset:5120
	ds_read_b128 v[224:227], v196 offset:6144
	ds_read_b128 v[228:231], v196 offset:7168
	global_load_lds_dwordx4 v146, s[16:17]
	s_add_i32 m0, s5, 0xe000
	s_nop 0
	global_load_lds_dwordx4 v148, s[16:17]
	s_waitcnt vmcnt(8)
	s_waitcnt lgkmcnt(0)
	s_setprio 1
	s_barrier
	v_mfma_f32_16x16x32_bf16 v[126:129], v[130:133], v[190:193], 0
	v_mfma_f32_16x16x32_bf16 v[122:125], v[154:157], v[190:193], 0
	v_mfma_f32_16x16x32_bf16 v[110:113], v[130:133], v[208:211], 0
	v_mfma_f32_16x16x32_bf16 v[106:109], v[154:157], v[208:211], 0
	v_mfma_f32_16x16x32_bf16 v[94:97], v[130:133], v[216:219], 0
	v_mfma_f32_16x16x32_bf16 v[90:93], v[154:157], v[216:219], 0
	v_mfma_f32_16x16x32_bf16 v[78:81], v[130:133], v[224:227], 0
	v_mfma_f32_16x16x32_bf16 v[74:77], v[154:157], v[224:227], 0
	v_mfma_f32_16x16x32_bf16 v[126:129], v[150:153], v[204:207], v[126:129]
	v_mfma_f32_16x16x32_bf16 v[122:125], v[158:161], v[204:207], v[122:125]
	v_mfma_f32_16x16x32_bf16 v[110:113], v[150:153], v[212:215], v[110:113]
	v_mfma_f32_16x16x32_bf16 v[106:109], v[158:161], v[212:215], v[106:109]
	v_mfma_f32_16x16x32_bf16 v[94:97], v[150:153], v[220:223], v[94:97]
	v_mfma_f32_16x16x32_bf16 v[90:93], v[158:161], v[220:223], v[90:93]
	v_mfma_f32_16x16x32_bf16 v[78:81], v[150:153], v[228:231], v[78:81]
	v_mfma_f32_16x16x32_bf16 v[74:77], v[158:161], v[228:231], v[74:77]
	v_mfma_f32_16x16x32_bf16 v[118:121], v[174:177], v[190:193], 0
	v_mfma_f32_16x16x32_bf16 v[114:117], v[182:185], v[190:193], 0
	v_mfma_f32_16x16x32_bf16 v[102:105], v[174:177], v[208:211], 0
	v_mfma_f32_16x16x32_bf16 v[98:101], v[182:185], v[208:211], 0
	v_mfma_f32_16x16x32_bf16 v[86:89], v[174:177], v[216:219], 0
	v_mfma_f32_16x16x32_bf16 v[82:85], v[182:185], v[216:219], 0
	v_mfma_f32_16x16x32_bf16 v[70:73], v[174:177], v[224:227], 0
	v_mfma_f32_16x16x32_bf16 v[66:69], v[182:185], v[224:227], 0
	v_mfma_f32_16x16x32_bf16 v[118:121], v[178:181], v[204:207], v[118:121]
	v_mfma_f32_16x16x32_bf16 v[114:117], v[186:189], v[204:207], v[114:117]
	v_mfma_f32_16x16x32_bf16 v[102:105], v[178:181], v[212:215], v[102:105]
	v_mfma_f32_16x16x32_bf16 v[98:101], v[186:189], v[212:215], v[98:101]
	v_mfma_f32_16x16x32_bf16 v[86:89], v[178:181], v[220:223], v[86:89]
	v_mfma_f32_16x16x32_bf16 v[82:85], v[186:189], v[220:223], v[82:85]
	v_mfma_f32_16x16x32_bf16 v[70:73], v[178:181], v[228:231], v[70:73]
	v_mfma_f32_16x16x32_bf16 v[66:69], v[186:189], v[228:231], v[66:69]
	s_barrier
	s_setprio 0
	s_add_i32 s37, s57, s4
	v_lshl_add_u64 v[170:171], s[42:43], 0, v[138:139]
	s_mov_b32 m0, s37
	ds_read_b128 v[190:193], v196 offset:16384
	ds_read_b128 v[204:207], v196 offset:17408
	ds_read_b128 v[208:211], v196 offset:18432
	ds_read_b128 v[212:215], v196 offset:19456
	ds_read_b128 v[216:219], v196 offset:20480
	ds_read_b128 v[220:223], v196 offset:21504
	ds_read_b128 v[224:227], v196 offset:22528
	ds_read_b128 v[228:231], v196 offset:23552
	global_load_lds_dwordx4 v[170:171], off
	s_add_i32 m0, s37, 0x2000
	s_add_u32 s74, s42, 0x40000
	v_lshl_add_u64 v[172:173], s[42:43], 0, v[134:135]
	s_addc_u32 s75, s43, 0
	s_add_i32 s29, s29, s4
	global_load_lds_dwordx4 v[172:173], off
	s_mov_b32 m0, s29
	v_lshl_add_u64 v[232:233], s[44:45], 0, v[136:137]
	global_load_lds_dwordx4 v138, s[74:75]
	s_add_i32 m0, s29, 0x2000
	s_nop 0
	global_load_lds_dwordx4 v134, s[74:75]
	v_lshl_add_u64 v[198:199], s[44:45], 0, v[140:141]
	s_mov_b32 m0, s5
	s_nop 0
	global_load_lds_dwordx4 v[198:199], off
	s_mov_b32 m0, s20
	s_nop 0
	global_load_lds_dwordx4 v[232:233], off
	s_lshl_b32 s101, s28, 14
	s_add_i32 s101, s101, s5
	s_add_u32 s100, s66, s101
	s_addc_u32 s101, s67, 0
	v_lshlrev_b32_e32 v2, 4, v163
	v_add_u32_e32 v3, 0x2000, v2
	s_add_i32 m0, s5, 0x20000
	s_nop 0
	global_load_lds_dwordx4 v2, s[100:101]
	s_add_i32 m0, s5, 0x22000
	s_nop 0
	global_load_lds_dwordx4 v3, s[100:101]
	s_waitcnt vmcnt(10)
	s_waitcnt lgkmcnt(0)
	s_setprio 1
	s_barrier
	v_mfma_f32_16x16x32_bf16 v[62:65], v[130:133], v[190:193], 0
	v_mfma_f32_16x16x32_bf16 v[58:61], v[154:157], v[190:193], 0
	v_mfma_f32_16x16x32_bf16 v[46:49], v[130:133], v[208:211], 0
	v_mfma_f32_16x16x32_bf16 v[42:45], v[154:157], v[208:211], 0
	v_mfma_f32_16x16x32_bf16 v[30:33], v[130:133], v[216:219], 0
	v_mfma_f32_16x16x32_bf16 v[26:29], v[154:157], v[216:219], 0
	v_mfma_f32_16x16x32_bf16 v[14:17], v[130:133], v[224:227], 0
	v_mfma_f32_16x16x32_bf16 v[10:13], v[154:157], v[224:227], 0
	v_mfma_f32_16x16x32_bf16 v[62:65], v[150:153], v[204:207], v[62:65]
	v_mfma_f32_16x16x32_bf16 v[58:61], v[158:161], v[204:207], v[58:61]
	v_mfma_f32_16x16x32_bf16 v[46:49], v[150:153], v[212:215], v[46:49]
	v_mfma_f32_16x16x32_bf16 v[42:45], v[158:161], v[212:215], v[42:45]
	v_mfma_f32_16x16x32_bf16 v[30:33], v[150:153], v[220:223], v[30:33]
	v_mfma_f32_16x16x32_bf16 v[26:29], v[158:161], v[220:223], v[26:29]
	v_mfma_f32_16x16x32_bf16 v[14:17], v[150:153], v[228:231], v[14:17]
	v_mfma_f32_16x16x32_bf16 v[10:13], v[158:161], v[228:231], v[10:13]
	v_mfma_f32_16x16x32_bf16 v[54:57], v[174:177], v[190:193], 0
	v_mfma_f32_16x16x32_bf16 v[50:53], v[182:185], v[190:193], 0
	v_mfma_f32_16x16x32_bf16 v[38:41], v[174:177], v[208:211], 0
	v_mfma_f32_16x16x32_bf16 v[34:37], v[182:185], v[208:211], 0
	v_mfma_f32_16x16x32_bf16 v[22:25], v[174:177], v[216:219], 0
	v_mfma_f32_16x16x32_bf16 v[18:21], v[182:185], v[216:219], 0
	v_mfma_f32_16x16x32_bf16 v[6:9], v[174:177], v[224:227], 0
	v_mfma_f32_16x16x32_bf16 v[2:5], v[182:185], v[224:227], 0
	v_mfma_f32_16x16x32_bf16 v[54:57], v[178:181], v[204:207], v[54:57]
	v_mfma_f32_16x16x32_bf16 v[50:53], v[186:189], v[204:207], v[50:53]
	v_mfma_f32_16x16x32_bf16 v[38:41], v[178:181], v[212:215], v[38:41]
	v_mfma_f32_16x16x32_bf16 v[34:37], v[186:189], v[212:215], v[34:37]
	v_mfma_f32_16x16x32_bf16 v[22:25], v[178:181], v[220:223], v[22:25]
	v_mfma_f32_16x16x32_bf16 v[18:21], v[186:189], v[220:223], v[18:21]
	v_mfma_f32_16x16x32_bf16 v[6:9], v[178:181], v[228:231], v[6:9]
	v_mfma_f32_16x16x32_bf16 v[2:5], v[186:189], v[228:231], v[2:5]
	s_barrier
	s_setprio 0
	s_add_i32 s29, 0, 0x18000
	v_add_u32_e32 v0, s29, v195
	s_add_i32 s37, 0, 0x1c000
	ds_read_b128 v[130:133], v0
	ds_read_b128 v[150:153], v0 offset:1024
	ds_read_b128 v[154:157], v0 offset:2048
	ds_read_b128 v[158:161], v0 offset:3072
	v_add_u32_e32 v0, s37, v195
	ds_read_b128 v[174:177], v0
	ds_read_b128 v[178:181], v0 offset:1024
	ds_read_b128 v[182:185], v0 offset:2048
	ds_read_b128 v[186:189], v0 offset:3072
	s_add_u32 s44, s44, 0x40000
	s_addc_u32 s45, s45, 0
	s_mov_b32 m0, s22
	ds_read_b128 v[190:193], v196 offset:32768
	ds_read_b128 v[204:207], v196 offset:33792
	ds_read_b128 v[208:211], v196 offset:34816
	ds_read_b128 v[212:215], v196 offset:35840
	ds_read_b128 v[216:219], v196 offset:36864
	ds_read_b128 v[220:223], v196 offset:37888
	ds_read_b128 v[224:227], v196 offset:38912
	ds_read_b128 v[228:231], v196 offset:39936
	global_load_lds_dwordx4 v140, s[44:45]
	s_mov_b32 m0, s23
	s_nop 0
	global_load_lds_dwordx4 v136, s[44:45]
	s_waitcnt vmcnt(10)
	s_waitcnt lgkmcnt(0)
	s_setprio 1
	s_barrier
	v_mfma_f32_16x16x32_bf16 v[126:129], v[130:133], v[190:193], v[126:129]
	v_mfma_f32_16x16x32_bf16 v[122:125], v[154:157], v[190:193], v[122:125]
	v_mfma_f32_16x16x32_bf16 v[110:113], v[130:133], v[208:211], v[110:113]
	v_mfma_f32_16x16x32_bf16 v[106:109], v[154:157], v[208:211], v[106:109]
	v_mfma_f32_16x16x32_bf16 v[94:97], v[130:133], v[216:219], v[94:97]
	v_mfma_f32_16x16x32_bf16 v[90:93], v[154:157], v[216:219], v[90:93]
	v_mfma_f32_16x16x32_bf16 v[78:81], v[130:133], v[224:227], v[78:81]
	v_mfma_f32_16x16x32_bf16 v[74:77], v[154:157], v[224:227], v[74:77]
	v_mfma_f32_16x16x32_bf16 v[126:129], v[150:153], v[204:207], v[126:129]
	v_mfma_f32_16x16x32_bf16 v[122:125], v[158:161], v[204:207], v[122:125]
	v_mfma_f32_16x16x32_bf16 v[110:113], v[150:153], v[212:215], v[110:113]
	v_mfma_f32_16x16x32_bf16 v[106:109], v[158:161], v[212:215], v[106:109]
	v_mfma_f32_16x16x32_bf16 v[94:97], v[150:153], v[220:223], v[94:97]
	v_mfma_f32_16x16x32_bf16 v[90:93], v[158:161], v[220:223], v[90:93]
	v_mfma_f32_16x16x32_bf16 v[78:81], v[150:153], v[228:231], v[78:81]
	v_mfma_f32_16x16x32_bf16 v[74:77], v[158:161], v[228:231], v[74:77]
	v_mfma_f32_16x16x32_bf16 v[118:121], v[174:177], v[190:193], v[118:121]
	v_mfma_f32_16x16x32_bf16 v[114:117], v[182:185], v[190:193], v[114:117]
	v_mfma_f32_16x16x32_bf16 v[102:105], v[174:177], v[208:211], v[102:105]
	v_mfma_f32_16x16x32_bf16 v[98:101], v[182:185], v[208:211], v[98:101]
	v_mfma_f32_16x16x32_bf16 v[86:89], v[174:177], v[216:219], v[86:89]
	v_mfma_f32_16x16x32_bf16 v[82:85], v[182:185], v[216:219], v[82:85]
	v_mfma_f32_16x16x32_bf16 v[70:73], v[174:177], v[224:227], v[70:73]
	v_mfma_f32_16x16x32_bf16 v[66:69], v[182:185], v[224:227], v[66:69]
	v_mfma_f32_16x16x32_bf16 v[118:121], v[178:181], v[204:207], v[118:121]
	v_mfma_f32_16x16x32_bf16 v[114:117], v[186:189], v[204:207], v[114:117]
	v_mfma_f32_16x16x32_bf16 v[102:105], v[178:181], v[212:215], v[102:105]
	v_mfma_f32_16x16x32_bf16 v[98:101], v[186:189], v[212:215], v[98:101]
	v_mfma_f32_16x16x32_bf16 v[86:89], v[178:181], v[220:223], v[86:89]
	v_mfma_f32_16x16x32_bf16 v[82:85], v[186:189], v[220:223], v[82:85]
	v_mfma_f32_16x16x32_bf16 v[70:73], v[178:181], v[228:231], v[70:73]
	v_mfma_f32_16x16x32_bf16 v[66:69], v[186:189], v[228:231], v[66:69]
	s_barrier
	s_setprio 0
	s_add_i32 s29, s29, s4
	v_lshl_add_u64 v[170:171], v[170:171], 0, s[24:25]
	s_mov_b32 m0, s29
	ds_read_b128 v[190:193], v196 offset:49152
	ds_read_b128 v[204:207], v196 offset:50176
	ds_read_b128 v[208:211], v196 offset:51200
	ds_read_b128 v[212:215], v196 offset:52224
	ds_read_b128 v[216:219], v196 offset:53248
	ds_read_b128 v[220:223], v196 offset:54272
	ds_read_b128 v[224:227], v196 offset:55296
	ds_read_b128 v[228:231], v196 offset:56320
	global_load_lds_dwordx4 v[170:171], off
	s_add_i32 m0, s29, 0x2000
	s_add_u32 s42, s42, 0x40080
	v_lshl_add_u64 v[170:171], v[172:173], 0, s[24:25]
	s_addc_u32 s43, s43, 0
	s_add_i32 s29, s37, s4
	global_load_lds_dwordx4 v[170:171], off
	s_mov_b32 m0, s29
	s_nop 0
	global_load_lds_dwordx4 v138, s[42:43]
	s_add_i32 m0, s29, 0x2000
	s_nop 0
	global_load_lds_dwordx4 v134, s[42:43]
	v_lshl_add_u64 v[170:171], v[198:199], 0, s[24:25]
	s_mov_b32 m0, s33
	s_nop 0
	global_load_lds_dwordx4 v[170:171], off
	v_lshl_add_u64 v[170:171], v[232:233], 0, s[24:25]
	s_mov_b32 m0, s72
	s_nop 0
	global_load_lds_dwordx4 v[170:171], off
	s_waitcnt vmcnt(8)
	s_waitcnt lgkmcnt(0)
	s_setprio 1
	s_barrier
	v_mfma_f32_16x16x32_bf16 v[62:65], v[130:133], v[190:193], v[62:65]
	v_mfma_f32_16x16x32_bf16 v[58:61], v[154:157], v[190:193], v[58:61]
	v_mfma_f32_16x16x32_bf16 v[46:49], v[130:133], v[208:211], v[46:49]
	v_mfma_f32_16x16x32_bf16 v[42:45], v[154:157], v[208:211], v[42:45]
	v_mfma_f32_16x16x32_bf16 v[30:33], v[130:133], v[216:219], v[30:33]
	v_mfma_f32_16x16x32_bf16 v[26:29], v[154:157], v[216:219], v[26:29]
	v_mfma_f32_16x16x32_bf16 v[14:17], v[130:133], v[224:227], v[14:17]
	v_mfma_f32_16x16x32_bf16 v[10:13], v[154:157], v[224:227], v[10:13]
	v_mfma_f32_16x16x32_bf16 v[62:65], v[150:153], v[204:207], v[62:65]
	v_mfma_f32_16x16x32_bf16 v[58:61], v[158:161], v[204:207], v[58:61]
	v_mfma_f32_16x16x32_bf16 v[46:49], v[150:153], v[212:215], v[46:49]
	v_mfma_f32_16x16x32_bf16 v[42:45], v[158:161], v[212:215], v[42:45]
	v_mfma_f32_16x16x32_bf16 v[30:33], v[150:153], v[220:223], v[30:33]
	v_mfma_f32_16x16x32_bf16 v[26:29], v[158:161], v[220:223], v[26:29]
	v_mfma_f32_16x16x32_bf16 v[14:17], v[150:153], v[228:231], v[14:17]
	v_mfma_f32_16x16x32_bf16 v[10:13], v[158:161], v[228:231], v[10:13]
	v_mfma_f32_16x16x32_bf16 v[54:57], v[174:177], v[190:193], v[54:57]
	v_mfma_f32_16x16x32_bf16 v[50:53], v[182:185], v[190:193], v[50:53]
	v_mfma_f32_16x16x32_bf16 v[38:41], v[174:177], v[208:211], v[38:41]
	v_mfma_f32_16x16x32_bf16 v[34:37], v[182:185], v[208:211], v[34:37]
	v_mfma_f32_16x16x32_bf16 v[22:25], v[174:177], v[216:219], v[22:25]
	v_mfma_f32_16x16x32_bf16 v[18:21], v[182:185], v[216:219], v[18:21]
	v_mfma_f32_16x16x32_bf16 v[6:9], v[174:177], v[224:227], v[6:9]
	v_mfma_f32_16x16x32_bf16 v[2:5], v[182:185], v[224:227], v[2:5]
	v_mfma_f32_16x16x32_bf16 v[54:57], v[178:181], v[204:207], v[54:57]
	v_mfma_f32_16x16x32_bf16 v[50:53], v[186:189], v[204:207], v[50:53]
	v_mfma_f32_16x16x32_bf16 v[38:41], v[178:181], v[212:215], v[38:41]
	v_mfma_f32_16x16x32_bf16 v[34:37], v[186:189], v[212:215], v[34:37]
	v_mfma_f32_16x16x32_bf16 v[22:25], v[178:181], v[220:223], v[22:25]
	v_mfma_f32_16x16x32_bf16 v[18:21], v[186:189], v[220:223], v[18:21]
	v_mfma_f32_16x16x32_bf16 v[6:9], v[178:181], v[228:231], v[6:9]
	v_mfma_f32_16x16x32_bf16 v[2:5], v[186:189], v[228:231], v[2:5]
	s_barrier
	s_setprio 0
	s_add_u32 s16, s16, 0x100
	s_addc_u32 s17, s17, 0
	s_add_u32 s48, s48, 0x100
	s_addc_u32 s49, s49, 0
	s_cmp_ge_i32 s56, s3
	s_mov_b32 s42, s56
	s_cbranch_scc0 .LBB7_523
	s_branch .Lpeelx_523
	.p2align	6

.Lpeel_1196:
	s_add_i32 s72, s42, 2
	s_add_u32 s29, s16, 0xfffc0080
	s_addc_u32 s37, s17, -1
	s_add_i32 s73, 0, 0x10000
	s_cmp_eq_u32 s55, s42
	s_cselect_b32 s53, s13, s37
	s_cselect_b32 s52, s15, s29
	v_add_u32_e32 v146, s73, v153
	s_cselect_b32 s43, s28, s57
	s_cselect_b32 s42, s39, s56
	s_add_i32 s29, 0, 0x14000
	ds_read_b128 v[130:133], v146
	ds_read_b128 v[156:159], v146 offset:1024
	ds_read_b128 v[174:177], v146 offset:2048
	ds_read_b128 v[178:181], v146 offset:3072
	v_add_u32_e32 v146, s29, v153
	ds_read_b128 v[182:185], v146
	ds_read_b128 v[186:189], v146 offset:1024
	ds_read_b128 v[190:193], v146 offset:2048
	ds_read_b128 v[194:197], v146 offset:3072
	s_add_i32 m0, s5, 0xc000
	ds_read_b128 v[204:207], v161
	ds_read_b128 v[208:211], v161 offset:1024
	ds_read_b128 v[212:215], v161 offset:2048
	ds_read_b128 v[216:219], v161 offset:3072
	ds_read_b128 v[220:223], v161 offset:4096
	ds_read_b128 v[224:227], v161 offset:5120
	ds_read_b128 v[228:231], v161 offset:6144
	ds_read_b128 v[232:235], v161 offset:7168
	global_load_lds_dwordx4 v142, s[16:17]
	s_add_i32 m0, s5, 0xe000
	s_nop 0
	global_load_lds_dwordx4 v144, s[16:17]
	s_waitcnt vmcnt(8)
	s_waitcnt lgkmcnt(0)
	s_setprio 1
	s_barrier
	v_mfma_f32_16x16x32_bf16 v[126:129], v[130:133], v[204:207], 0
	v_mfma_f32_16x16x32_bf16 v[122:125], v[174:177], v[204:207], 0
	v_mfma_f32_16x16x32_bf16 v[110:113], v[130:133], v[212:215], 0
	v_mfma_f32_16x16x32_bf16 v[106:109], v[174:177], v[212:215], 0
	v_mfma_f32_16x16x32_bf16 v[94:97], v[130:133], v[220:223], 0
	v_mfma_f32_16x16x32_bf16 v[90:93], v[174:177], v[220:223], 0
	v_mfma_f32_16x16x32_bf16 v[78:81], v[130:133], v[228:231], 0
	v_mfma_f32_16x16x32_bf16 v[74:77], v[174:177], v[228:231], 0
	v_mfma_f32_16x16x32_bf16 v[126:129], v[156:159], v[208:211], v[126:129]
	v_mfma_f32_16x16x32_bf16 v[122:125], v[178:181], v[208:211], v[122:125]
	v_mfma_f32_16x16x32_bf16 v[110:113], v[156:159], v[216:219], v[110:113]
	v_mfma_f32_16x16x32_bf16 v[106:109], v[178:181], v[216:219], v[106:109]
	v_mfma_f32_16x16x32_bf16 v[94:97], v[156:159], v[224:227], v[94:97]
	v_mfma_f32_16x16x32_bf16 v[90:93], v[178:181], v[224:227], v[90:93]
	v_mfma_f32_16x16x32_bf16 v[78:81], v[156:159], v[232:235], v[78:81]
	v_mfma_f32_16x16x32_bf16 v[74:77], v[178:181], v[232:235], v[74:77]
	v_mfma_f32_16x16x32_bf16 v[118:121], v[182:185], v[204:207], 0
	v_mfma_f32_16x16x32_bf16 v[114:117], v[190:193], v[204:207], 0
	v_mfma_f32_16x16x32_bf16 v[102:105], v[182:185], v[212:215], 0
	v_mfma_f32_16x16x32_bf16 v[98:101], v[190:193], v[212:215], 0
	v_mfma_f32_16x16x32_bf16 v[86:89], v[182:185], v[220:223], 0
	v_mfma_f32_16x16x32_bf16 v[82:85], v[190:193], v[220:223], 0
	v_mfma_f32_16x16x32_bf16 v[70:73], v[182:185], v[228:231], 0
	v_mfma_f32_16x16x32_bf16 v[66:69], v[190:193], v[228:231], 0
	v_mfma_f32_16x16x32_bf16 v[118:121], v[186:189], v[208:211], v[118:121]
	v_mfma_f32_16x16x32_bf16 v[114:117], v[194:197], v[208:211], v[114:117]
	v_mfma_f32_16x16x32_bf16 v[102:105], v[186:189], v[216:219], v[102:105]
	v_mfma_f32_16x16x32_bf16 v[98:101], v[194:197], v[216:219], v[98:101]
	v_mfma_f32_16x16x32_bf16 v[86:89], v[186:189], v[224:227], v[86:89]
	v_mfma_f32_16x16x32_bf16 v[82:85], v[194:197], v[224:227], v[82:85]
	v_mfma_f32_16x16x32_bf16 v[70:73], v[186:189], v[232:235], v[70:73]
	v_mfma_f32_16x16x32_bf16 v[66:69], v[194:197], v[232:235], v[66:69]
	s_barrier
	s_setprio 0
	s_add_i32 s37, s73, s4
	v_lshl_add_u64 v[146:147], s[42:43], 0, v[0:1]
	s_mov_b32 m0, s37
	ds_read_b128 v[204:207], v161 offset:16384
	ds_read_b128 v[208:211], v161 offset:17408
	ds_read_b128 v[212:215], v161 offset:18432
	ds_read_b128 v[216:219], v161 offset:19456
	ds_read_b128 v[220:223], v161 offset:20480
	ds_read_b128 v[224:227], v161 offset:21504
	ds_read_b128 v[228:231], v161 offset:22528
	ds_read_b128 v[232:235], v161 offset:23552
	global_load_lds_dwordx4 v[146:147], off
	s_add_i32 m0, s37, 0x2000
	s_add_u32 s74, s42, 0x40000
	v_lshl_add_u64 v[150:151], s[42:43], 0, v[134:135]
	s_addc_u32 s75, s43, 0
	s_add_i32 s29, s29, s4
	global_load_lds_dwordx4 v[150:151], off
	s_mov_b32 m0, s29
	v_lshl_add_u64 v[172:173], s[52:53], 0, v[136:137]
	global_load_lds_dwordx4 v0, s[74:75]
	s_add_i32 m0, s29, 0x2000
	s_nop 0
	global_load_lds_dwordx4 v134, s[74:75]
	v_lshl_add_u64 v[170:171], s[52:53], 0, v[138:139]
	s_mov_b32 m0, s5
	s_nop 0
	global_load_lds_dwordx4 v[170:171], off
	s_mov_b32 m0, s20
	s_nop 0
	global_load_lds_dwordx4 v[172:173], off
	s_lshl_b32 s101, s10, 14
	s_add_i32 s101, s101, s5
	s_add_u32 s100, s66, s101
	s_addc_u32 s101, s67, 0
	v_lshlrev_b32_e32 v2, 4, v163
	v_add_u32_e32 v3, 0x2000, v2
	s_add_i32 m0, s5, 0x20000
	s_nop 0
	global_load_lds_dwordx4 v2, s[100:101]
	s_add_i32 m0, s5, 0x22000
	s_nop 0
	global_load_lds_dwordx4 v3, s[100:101]
	s_waitcnt vmcnt(10)
	s_waitcnt lgkmcnt(0)
	s_setprio 1
	s_barrier
	v_mfma_f32_16x16x32_bf16 v[62:65], v[130:133], v[204:207], 0
	v_mfma_f32_16x16x32_bf16 v[58:61], v[174:177], v[204:207], 0
	v_mfma_f32_16x16x32_bf16 v[46:49], v[130:133], v[212:215], 0
	v_mfma_f32_16x16x32_bf16 v[42:45], v[174:177], v[212:215], 0
	v_mfma_f32_16x16x32_bf16 v[30:33], v[130:133], v[220:223], 0
	v_mfma_f32_16x16x32_bf16 v[26:29], v[174:177], v[220:223], 0
	v_mfma_f32_16x16x32_bf16 v[14:17], v[130:133], v[228:231], 0
	v_mfma_f32_16x16x32_bf16 v[10:13], v[174:177], v[228:231], 0
	v_mfma_f32_16x16x32_bf16 v[62:65], v[156:159], v[208:211], v[62:65]
	v_mfma_f32_16x16x32_bf16 v[58:61], v[178:181], v[208:211], v[58:61]
	v_mfma_f32_16x16x32_bf16 v[46:49], v[156:159], v[216:219], v[46:49]
	v_mfma_f32_16x16x32_bf16 v[42:45], v[178:181], v[216:219], v[42:45]
	v_mfma_f32_16x16x32_bf16 v[30:33], v[156:159], v[224:227], v[30:33]
	v_mfma_f32_16x16x32_bf16 v[26:29], v[178:181], v[224:227], v[26:29]
	v_mfma_f32_16x16x32_bf16 v[14:17], v[156:159], v[232:235], v[14:17]
	v_mfma_f32_16x16x32_bf16 v[10:13], v[178:181], v[232:235], v[10:13]
	v_mfma_f32_16x16x32_bf16 v[54:57], v[182:185], v[204:207], 0
	v_mfma_f32_16x16x32_bf16 v[50:53], v[190:193], v[204:207], 0
	v_mfma_f32_16x16x32_bf16 v[38:41], v[182:185], v[212:215], 0
	v_mfma_f32_16x16x32_bf16 v[34:37], v[190:193], v[212:215], 0
	v_mfma_f32_16x16x32_bf16 v[22:25], v[182:185], v[220:223], 0
	v_mfma_f32_16x16x32_bf16 v[18:21], v[190:193], v[220:223], 0
	v_mfma_f32_16x16x32_bf16 v[6:9], v[182:185], v[228:231], 0
	v_mfma_f32_16x16x32_bf16 v[2:5], v[190:193], v[228:231], 0
	v_mfma_f32_16x16x32_bf16 v[54:57], v[186:189], v[208:211], v[54:57]
	v_mfma_f32_16x16x32_bf16 v[50:53], v[194:197], v[208:211], v[50:53]
	v_mfma_f32_16x16x32_bf16 v[38:41], v[186:189], v[216:219], v[38:41]
	v_mfma_f32_16x16x32_bf16 v[34:37], v[194:197], v[216:219], v[34:37]
	v_mfma_f32_16x16x32_bf16 v[22:25], v[186:189], v[224:227], v[22:25]
	v_mfma_f32_16x16x32_bf16 v[18:21], v[194:197], v[224:227], v[18:21]
	v_mfma_f32_16x16x32_bf16 v[6:9], v[186:189], v[232:235], v[6:9]
	v_mfma_f32_16x16x32_bf16 v[2:5], v[194:197], v[232:235], v[2:5]
	s_barrier
	s_setprio 0
	s_add_i32 s29, 0, 0x18000
	v_add_u32_e32 v148, s29, v153
	s_add_i32 s37, 0, 0x1c000
	ds_read_b128 v[130:133], v148
	ds_read_b128 v[156:159], v148 offset:1024
	ds_read_b128 v[174:177], v148 offset:2048
	ds_read_b128 v[178:181], v148 offset:3072
	v_add_u32_e32 v148, s37, v153
	ds_read_b128 v[182:185], v148
	ds_read_b128 v[186:189], v148 offset:1024
	ds_read_b128 v[190:193], v148 offset:2048
	ds_read_b128 v[194:197], v148 offset:3072
	s_add_u32 s52, s52, 0x40000
	s_addc_u32 s53, s53, 0
	s_mov_b32 m0, s22
	ds_read_b128 v[204:207], v161 offset:32768
	ds_read_b128 v[208:211], v161 offset:33792
	ds_read_b128 v[212:215], v161 offset:34816
	ds_read_b128 v[216:219], v161 offset:35840
	ds_read_b128 v[220:223], v161 offset:36864
	ds_read_b128 v[224:227], v161 offset:37888
	ds_read_b128 v[228:231], v161 offset:38912
	ds_read_b128 v[232:235], v161 offset:39936
	global_load_lds_dwordx4 v138, s[52:53]
	s_mov_b32 m0, s23
	s_nop 0
	global_load_lds_dwordx4 v136, s[52:53]
	s_waitcnt vmcnt(10)
	s_waitcnt lgkmcnt(0)
	s_setprio 1
	s_barrier
	v_mfma_f32_16x16x32_bf16 v[126:129], v[130:133], v[204:207], v[126:129]
	v_mfma_f32_16x16x32_bf16 v[122:125], v[174:177], v[204:207], v[122:125]
	v_mfma_f32_16x16x32_bf16 v[110:113], v[130:133], v[212:215], v[110:113]
	v_mfma_f32_16x16x32_bf16 v[106:109], v[174:177], v[212:215], v[106:109]
	v_mfma_f32_16x16x32_bf16 v[94:97], v[130:133], v[220:223], v[94:97]
	v_mfma_f32_16x16x32_bf16 v[90:93], v[174:177], v[220:223], v[90:93]
	v_mfma_f32_16x16x32_bf16 v[78:81], v[130:133], v[228:231], v[78:81]
	v_mfma_f32_16x16x32_bf16 v[74:77], v[174:177], v[228:231], v[74:77]
	v_mfma_f32_16x16x32_bf16 v[126:129], v[156:159], v[208:211], v[126:129]
	v_mfma_f32_16x16x32_bf16 v[122:125], v[178:181], v[208:211], v[122:125]
	v_mfma_f32_16x16x32_bf16 v[110:113], v[156:159], v[216:219], v[110:113]
	v_mfma_f32_16x16x32_bf16 v[106:109], v[178:181], v[216:219], v[106:109]
	v_mfma_f32_16x16x32_bf16 v[94:97], v[156:159], v[224:227], v[94:97]
	v_mfma_f32_16x16x32_bf16 v[90:93], v[178:181], v[224:227], v[90:93]
	v_mfma_f32_16x16x32_bf16 v[78:81], v[156:159], v[232:235], v[78:81]
	v_mfma_f32_16x16x32_bf16 v[74:77], v[178:181], v[232:235], v[74:77]
	v_mfma_f32_16x16x32_bf16 v[118:121], v[182:185], v[204:207], v[118:121]
	v_mfma_f32_16x16x32_bf16 v[114:117], v[190:193], v[204:207], v[114:117]
	v_mfma_f32_16x16x32_bf16 v[102:105], v[182:185], v[212:215], v[102:105]
	v_mfma_f32_16x16x32_bf16 v[98:101], v[190:193], v[212:215], v[98:101]
	v_mfma_f32_16x16x32_bf16 v[86:89], v[182:185], v[220:223], v[86:89]
	v_mfma_f32_16x16x32_bf16 v[82:85], v[190:193], v[220:223], v[82:85]
	v_mfma_f32_16x16x32_bf16 v[70:73], v[182:185], v[228:231], v[70:73]
	v_mfma_f32_16x16x32_bf16 v[66:69], v[190:193], v[228:231], v[66:69]
	v_mfma_f32_16x16x32_bf16 v[118:121], v[186:189], v[208:211], v[118:121]
	v_mfma_f32_16x16x32_bf16 v[114:117], v[194:197], v[208:211], v[114:117]
	v_mfma_f32_16x16x32_bf16 v[102:105], v[186:189], v[216:219], v[102:105]
	v_mfma_f32_16x16x32_bf16 v[98:101], v[194:197], v[216:219], v[98:101]
	v_mfma_f32_16x16x32_bf16 v[86:89], v[186:189], v[224:227], v[86:89]
	v_mfma_f32_16x16x32_bf16 v[82:85], v[194:197], v[224:227], v[82:85]
	v_mfma_f32_16x16x32_bf16 v[70:73], v[186:189], v[232:235], v[70:73]
	v_mfma_f32_16x16x32_bf16 v[66:69], v[194:197], v[232:235], v[66:69]
	s_barrier
	s_setprio 0
	s_add_i32 s29, s29, s4
	v_lshl_add_u64 v[146:147], v[146:147], 0, s[24:25]
	s_mov_b32 m0, s29
	ds_read_b128 v[204:207], v161 offset:49152
	ds_read_b128 v[208:211], v161 offset:50176
	ds_read_b128 v[212:215], v161 offset:51200
	ds_read_b128 v[216:219], v161 offset:52224
	ds_read_b128 v[220:223], v161 offset:53248
	ds_read_b128 v[224:227], v161 offset:54272
	ds_read_b128 v[228:231], v161 offset:55296
	ds_read_b128 v[232:235], v161 offset:56320
	global_load_lds_dwordx4 v[146:147], off
	s_add_i32 m0, s29, 0x2000
	s_add_u32 s42, s42, 0x40080
	v_lshl_add_u64 v[146:147], v[150:151], 0, s[24:25]
	s_addc_u32 s43, s43, 0
	s_add_i32 s29, s37, s4
	global_load_lds_dwordx4 v[146:147], off
	s_mov_b32 m0, s29
	s_nop 0
	global_load_lds_dwordx4 v0, s[42:43]
	s_add_i32 m0, s29, 0x2000
	s_nop 0
	global_load_lds_dwordx4 v134, s[42:43]
	v_lshl_add_u64 v[146:147], v[170:171], 0, s[24:25]
	s_mov_b32 m0, s31
	s_nop 0
	global_load_lds_dwordx4 v[146:147], off
	v_lshl_add_u64 v[146:147], v[172:173], 0, s[24:25]
	s_mov_b32 m0, s33
	s_nop 0
	global_load_lds_dwordx4 v[146:147], off
	s_waitcnt vmcnt(8)
	s_waitcnt lgkmcnt(0)
	s_setprio 1
	s_barrier
	v_mfma_f32_16x16x32_bf16 v[62:65], v[130:133], v[204:207], v[62:65]
	v_mfma_f32_16x16x32_bf16 v[58:61], v[174:177], v[204:207], v[58:61]
	v_mfma_f32_16x16x32_bf16 v[46:49], v[130:133], v[212:215], v[46:49]
	v_mfma_f32_16x16x32_bf16 v[42:45], v[174:177], v[212:215], v[42:45]
	v_mfma_f32_16x16x32_bf16 v[30:33], v[130:133], v[220:223], v[30:33]
	v_mfma_f32_16x16x32_bf16 v[26:29], v[174:177], v[220:223], v[26:29]
	v_mfma_f32_16x16x32_bf16 v[14:17], v[130:133], v[228:231], v[14:17]
	v_mfma_f32_16x16x32_bf16 v[10:13], v[174:177], v[228:231], v[10:13]
	v_mfma_f32_16x16x32_bf16 v[62:65], v[156:159], v[208:211], v[62:65]
	v_mfma_f32_16x16x32_bf16 v[58:61], v[178:181], v[208:211], v[58:61]
	v_mfma_f32_16x16x32_bf16 v[46:49], v[156:159], v[216:219], v[46:49]
	v_mfma_f32_16x16x32_bf16 v[42:45], v[178:181], v[216:219], v[42:45]
	v_mfma_f32_16x16x32_bf16 v[30:33], v[156:159], v[224:227], v[30:33]
	v_mfma_f32_16x16x32_bf16 v[26:29], v[178:181], v[224:227], v[26:29]
	v_mfma_f32_16x16x32_bf16 v[14:17], v[156:159], v[232:235], v[14:17]
	v_mfma_f32_16x16x32_bf16 v[10:13], v[178:181], v[232:235], v[10:13]
	v_mfma_f32_16x16x32_bf16 v[54:57], v[182:185], v[204:207], v[54:57]
	v_mfma_f32_16x16x32_bf16 v[50:53], v[190:193], v[204:207], v[50:53]
	v_mfma_f32_16x16x32_bf16 v[38:41], v[182:185], v[212:215], v[38:41]
	v_mfma_f32_16x16x32_bf16 v[34:37], v[190:193], v[212:215], v[34:37]
	v_mfma_f32_16x16x32_bf16 v[22:25], v[182:185], v[220:223], v[22:25]
	v_mfma_f32_16x16x32_bf16 v[18:21], v[190:193], v[220:223], v[18:21]
	v_mfma_f32_16x16x32_bf16 v[6:9], v[182:185], v[228:231], v[6:9]
	v_mfma_f32_16x16x32_bf16 v[2:5], v[190:193], v[228:231], v[2:5]
	v_mfma_f32_16x16x32_bf16 v[54:57], v[186:189], v[208:211], v[54:57]
	v_mfma_f32_16x16x32_bf16 v[50:53], v[194:197], v[208:211], v[50:53]
	v_mfma_f32_16x16x32_bf16 v[38:41], v[186:189], v[216:219], v[38:41]
	v_mfma_f32_16x16x32_bf16 v[34:37], v[194:197], v[216:219], v[34:37]
	v_mfma_f32_16x16x32_bf16 v[22:25], v[186:189], v[224:227], v[22:25]
	v_mfma_f32_16x16x32_bf16 v[18:21], v[194:197], v[224:227], v[18:21]
	v_mfma_f32_16x16x32_bf16 v[6:9], v[186:189], v[232:235], v[6:9]
	v_mfma_f32_16x16x32_bf16 v[2:5], v[194:197], v[232:235], v[2:5]
	s_barrier
	s_setprio 0
	s_add_u32 s16, s16, 0x100
	s_addc_u32 s17, s17, 0
	s_add_u32 s56, s56, 0x100
	s_addc_u32 s57, s57, 0
	s_cmp_ge_i32 s72, s3
	s_mov_b32 s42, s72
	s_cbranch_scc0 .LBB7_1196
	s_branch .Lpeelx_1196
	.p2align	6
